# attention: static s_setprio 1 for waves 4-7 during the attention unit loop (de-phase SIMD wave pairs)
# speedup vs baseline: 1.0037x; 1.0037x over previous
.LBB0_450:
	s_or_b64 exec, exec, s[4:5]
	v_readlane_b32 s0, v254, 13
	v_mov_b32_e32 v1, v220
	v_readlane_b32 s1, v254, 14
	s_waitcnt lgkmcnt(0)
	s_barrier
	s_andn2_b64 vcc, exec, s[0:1]
	v_readfirstlane_b32 s3, v1
	s_cbranch_vccnz .LBB0_505
	s_cmpk_lt_u32 s3, 0x100
	s_cbranch_scc1 .Lattn_prio_skip
	s_setprio 1
.Lattn_prio_skip:
	v_ashrrev_i32_e32 v209, 3, v1
	s_movk_i32 s6, 0x90
	s_and_b64 s[4:5], s[60:61], exec
	v_and_b32_e32 v5, 7, v1
	v_mul_lo_u32 v6, v209, s6
	v_bfe_u32 v3, v1, 5, 1
	v_add_u32_e32 v6, 0, v6
	v_lshlrev_b32_e32 v7, 4, v5
	s_movk_i32 s4, 0xff72
	v_and_b32_e32 v193, 31, v1
	v_lshlrev_b32_e32 v2, 3, v3
	v_mad_u64_u32 v[8:9], s[4:5], v209, s4, v[6:7]
	v_and_or_b32 v212, v1, 63, 32
	s_cselect_b32 s0, 8, 0
	s_cselect_b32 s1, 0x200, 0
	s_ashr_i32 s26, s3, 7
	s_and_b32 s3, s3, 64
	v_lshlrev_b32_e32 v192, 3, v5
	v_lshlrev_b32_e32 v4, 2, v3
	v_mad_u32_u24 v9, v193, s6, 0
	v_lshlrev_b32_e32 v3, 4, v3
	v_mad_u32_u24 v1, v212, s6, 0
	v_add_u32_e32 v10, 0, v2
	v_mul_u32_u24_e32 v5, 0x440, v5
	v_mul_u32_u24_e32 v11, 0x88, v193
	v_mul_u32_u24_e32 v12, 0x88, v212
	v_or_b32_e32 v208, s3, v193
	v_add_u32_e32 v210, 64, v209
	v_add_u32_e32 v211, 0x80, v209
	v_add_u32_e32 v213, 0xc0, v209
	v_sub_u32_e32 v214, s3, v4
	s_xor_b32 s27, s3, 0xffffff7f
	s_lshl_b32 s30, s0, 2
	v_lshlrev_b32_e32 v194, 1, v2
	v_add_u32_e32 v215, v6, v7
	v_mul_u32_u24_e32 v216, 0xc0, v209
	v_add_u32_e32 v216, v216, v7
	v_add_u32_e32 v217, v9, v3
	v_add_u32_e32 v218, v1, v3
	v_lshlrev_b32_e32 v196, 1, v4
	v_bfe_u32 v10, v220, 2, 2
	v_bfe_u32 v11, v220, 5, 1
	v_lshl_add_u32 v10, v11, 2, v10
	v_mul_u32_u24_e32 v10, 0xc0, v10
	v_bfe_u32 v11, v220, 4, 1
	v_lshl_add_u32 v10, v11, 5, v10
	v_and_b32_e32 v11, 3, v220
	v_lshl_add_u32 v219, v11, 3, v10
	s_mov_b32 s31, s2
	s_branch .LBB0_454

.LBB0_505:
	s_setprio 0
	v_mov_b32_e32 v48, v220
	s_mov_b64 s[4:5], -1
	v_readfirstlane_b32 s0, v48
	s_ashr_i32 s35, s0, 6
	v_readlane_b32 s0, v254, 0
	v_readlane_b32 s1, v254, 1
	v_and_b32_e32 v39, 63, v48
	s_andn2_b64 vcc, exec, s[0:1]
	s_cbranch_vccnz .LBB0_546
	v_readlane_b32 s0, v254, 15
	v_readlane_b32 s1, v254, 16
	s_mov_b32 s34, 0x358637bd
	s_andn2_b64 vcc, exec, s[0:1]
	s_cbranch_vccnz .LBB0_545
	v_readlane_b32 s0, v255, 31
	v_readlane_b32 s1, v255, 32
	s_and_b64 s[4:5], s[0:1], exec
	v_ashrrev_i32_e32 v3, 8, v48
	s_cselect_b32 s40, 0x7c00, 0
	s_cselect_b32 s0, 0x100, 0
	v_lshlrev_b32_e32 v5, 13, v3
	v_lshlrev_b32_e32 v55, 4, v3
	v_lshlrev_b32_e32 v3, 14, v3
	s_add_i32 s1, 0, 0x10000
	v_add_u32_e32 v10, s1, v3
	v_readlane_b32 s1, v255, 9
	v_and_b32_e32 v34, 0xff, v48
	v_ashrrev_i32_e32 v1, 5, v48
	v_add_u32_e32 v11, s1, v3
	v_readlane_b32 s1, v255, 10
	v_and_b32_e32 v2, 31, v48
	v_lshlrev_b32_e32 v36, 3, v2
	v_add_u32_e32 v12, s1, v3
	v_readlane_b32 s1, v255, 11
	v_add_u32_e32 v35, 16, v1
	v_add_u32_e32 v37, 32, v1
	v_add_u32_e32 v13, s1, v3
	v_readlane_b32 s1, v255, 12
	v_add_u32_e32 v49, 48, v1
	v_lshlrev_b32_e32 v2, 4, v2
	v_add_u32_e32 v14, s1, v3
	v_readlane_b32 s1, v255, 13
	v_lshlrev_b32_e32 v52, 9, v1
	v_lshlrev_b32_e32 v6, 1, v34
	s_lshl_b32 s41, s35, 2
	v_add_u32_e32 v15, s1, v3
	v_readlane_b32 s1, v255, 14
	v_lshlrev_b32_e32 v38, 2, v39
	v_add_u32_e32 v51, 0, v2
	v_add_u32_e32 v4, 0, v52
	v_add3_u32 v53, 0, v5, v6
	v_lshlrev_b32_e32 v5, 9, v35
	v_lshlrev_b32_e32 v6, 9, v37
	v_lshlrev_b32_e32 v7, 9, v49
	v_lshlrev_b32_e32 v8, 2, v34
	v_add_u32_e32 v9, 0, v3
	v_add_u32_e32 v3, s1, v3
	s_or_b32 s45, s41, 1
	s_or_b32 s58, s41, 2
	s_or_b32 s60, s41, 3
	v_cmp_gt_i32_e32 vcc, 62, v1
	v_cmp_gt_i32_e64 s[12:13], 46, v1
	v_cmp_gt_i32_e64 s[4:5], 30, v1
	v_cmp_gt_i32_e64 s[6:7], 14, v1
	v_add_u32_e32 v50, -8, v1
	v_bfe_u32 v54, v48, 6, 2
	v_cmp_lt_u32_e64 s[8:9], 63, v34
	v_lshl_add_u32 v56, v39, 4, 0
	s_lshl_b32 s44, s35, 12
	s_lshl_b32 s46, s45, 10
	s_lshl_b32 s59, s58, 10
	s_lshl_b32 s61, s60, 10
	s_lshl_b32 s64, s0, 2
	v_lshlrev_b32_e32 v40, 2, v34
	v_lshlrev_b32_e32 v57, 2, v38
	v_add_u32_e32 v58, v51, v5
	v_add_u32_e32 v59, v51, v6
	v_add_u32_e32 v60, v51, v7
	v_add_u32_e32 v61, v4, v2
	v_add_u32_e32 v62, v9, v8
	v_add_u32_e32 v63, v10, v8
	v_add_u32_e32 v64, v11, v8
	v_add_u32_e32 v65, v12, v8
	v_add_u32_e32 v66, v13, v8
	v_add_u32_e32 v67, v14, v8
	v_add_u32_e32 v68, v15, v8
	v_add_u32_e32 v69, v3, v8
	s_mov_b32 s65, s2
	s_branch .LBB0_509
